# SwiGLU epilogue: (1+e)*q denominators computed with packed v_pk_fma_f32 (8 scalar fma -> 4 packed per row group), bit-identical
# speedup vs baseline: 1.0125x; 1.0125x over previous
.LBB0_155:
	ds_read_b128 v[160:163], v155
	ds_read_b128 v[164:167], v155 offset:1024
	ds_read_b128 v[168:171], v155 offset:2048
	ds_read_b128 v[172:175], v155 offset:3072
	ds_read_b128 v[176:179], v156
	ds_read_b128 v[180:183], v156 offset:1024
	ds_read_b128 v[184:187], v156 offset:2048
	ds_read_b128 v[188:191], v156 offset:3072
	ds_read_b128 v[192:195], v157
	ds_read_b128 v[196:199], v157 offset:1024
	ds_read_b128 v[200:203], v157 offset:2048
	ds_read_b128 v[204:207], v157 offset:3072
	ds_read_b128 v[208:211], v157 offset:4096
	ds_read_b128 v[212:215], v157 offset:5120
	ds_read_b128 v[216:219], v157 offset:6144
	ds_read_b128 v[220:223], v157 offset:7168
	s_andn2_b64 vcc, exec, s[4:5]
	s_waitcnt vmcnt(0)
	v_fmamk_f32 v239, v149, 0x3a800000, v158
	v_rsq_f32_e32 v149, v239
	s_nop 0
	v_mul_f32_e32 v252, 0xbfb8aa3b, v149
	v_pk_mul_f32 v[120:121], v[120:121], v[252:253] op_sel_hi:[1,0]
	v_pk_mul_f32 v[118:119], v[118:119], v[252:253] op_sel_hi:[1,0]
	v_pk_mul_f32 v[116:117], v[116:117], v[252:253] op_sel_hi:[1,0]
	v_pk_mul_f32 v[114:115], v[114:115], v[252:253] op_sel_hi:[1,0]
	v_exp_f32_e32 v118, v118
	v_exp_f32_e32 v119, v119
	v_exp_f32_e32 v120, v120
	v_exp_f32_e32 v121, v121
	v_exp_f32_e32 v114, v114
	v_exp_f32_e32 v115, v115
	v_exp_f32_e32 v116, v116
	v_exp_f32_e32 v117, v117
	v_pk_fma_f32 v[118:119], v[118:119], v[238:239], v[238:239] op_sel:[0,1,1] op_sel_hi:[1,1,1]
	v_pk_fma_f32 v[120:121], v[120:121], v[238:239], v[238:239] op_sel:[0,1,1] op_sel_hi:[1,1,1]
	v_pk_fma_f32 v[250:251], v[114:115], v[238:239], v[238:239] op_sel:[0,1,1] op_sel_hi:[1,1,1]
	v_pk_fma_f32 v[254:255], v[116:117], v[238:239], v[238:239] op_sel:[0,1,1] op_sel_hi:[1,1,1]
	v_rcp_f32_e32 v114, v118
	v_rcp_f32_e32 v115, v119
	v_rcp_f32_e32 v116, v120
	v_rcp_f32_e32 v117, v121
	v_rcp_f32_e32 v118, v250
	v_rcp_f32_e32 v119, v251
	v_rcp_f32_e32 v120, v254
	v_rcp_f32_e32 v121, v255
	v_pk_mul_f32 v[116:117], v[128:129], v[116:117]
	v_pk_mul_f32 v[114:115], v[126:127], v[114:115]
	v_pk_mul_f32 v[120:121], v[124:125], v[120:121]
	v_pk_mul_f32 v[118:119], v[244:245], v[118:119]
	v_cvt_pk_bf16_f32 v114, v114, v115
	v_cvt_pk_bf16_f32 v115, v116, v117
	v_cvt_pk_bf16_f32 v116, v118, v119
	v_cvt_pk_bf16_f32 v117, v120, v121
	global_store_dwordx4 v[248:249], v[114:117], off
	v_fmamk_f32 v239, v232, 0x3a800000, v158
	v_rsq_f32_e32 v121, v239
	s_nop 0
	v_mul_f32_e32 v120, 0xbfb8aa3b, v121
	v_pk_mul_f32 v[108:109], v[108:109], v[120:121] op_sel_hi:[1,0]
	v_pk_mul_f32 v[106:107], v[106:107], v[120:121] op_sel_hi:[1,0]
	v_pk_mul_f32 v[100:101], v[100:101], v[120:121] op_sel_hi:[1,0]
	v_pk_mul_f32 v[98:99], v[98:99], v[120:121] op_sel_hi:[1,0]
	v_exp_f32_e32 v106, v106
	v_exp_f32_e32 v107, v107
	v_exp_f32_e32 v108, v108
	v_exp_f32_e32 v109, v109
	v_exp_f32_e32 v98, v98
	v_exp_f32_e32 v99, v99
	v_exp_f32_e32 v100, v100
	v_exp_f32_e32 v101, v101
	v_pk_fma_f32 v[106:107], v[106:107], v[238:239], v[238:239] op_sel:[0,1,1] op_sel_hi:[1,1,1]
	v_pk_fma_f32 v[108:109], v[108:109], v[238:239], v[238:239] op_sel:[0,1,1] op_sel_hi:[1,1,1]
	v_pk_fma_f32 v[250:251], v[98:99], v[238:239], v[238:239] op_sel:[0,1,1] op_sel_hi:[1,1,1]
	v_pk_fma_f32 v[254:255], v[100:101], v[238:239], v[238:239] op_sel:[0,1,1] op_sel_hi:[1,1,1]
	v_rcp_f32_e32 v98, v106
	v_rcp_f32_e32 v99, v107
	v_rcp_f32_e32 v100, v108
	v_rcp_f32_e32 v101, v109
	v_rcp_f32_e32 v106, v250
	v_rcp_f32_e32 v107, v251
	v_rcp_f32_e32 v108, v254
	v_rcp_f32_e32 v109, v255
	v_pk_mul_f32 v[100:101], v[112:113], v[100:101]
	v_pk_mul_f32 v[98:99], v[110:111], v[98:99]
	v_pk_mul_f32 v[104:105], v[104:105], v[108:109]
	v_pk_mul_f32 v[102:103], v[102:103], v[106:107]
	s_mov_b32 s98, 0x16000
	v_lshl_add_u64 v[116:117], v[240:241], 0, s[98:99]
	v_cvt_pk_bf16_f32 v98, v98, v99
	v_cvt_pk_bf16_f32 v99, v100, v101
	v_cvt_pk_bf16_f32 v100, v102, v103
	v_cvt_pk_bf16_f32 v101, v104, v105
	global_store_dwordx4 v[116:117], v[98:101], off
	v_fmamk_f32 v239, v233, 0x3a800000, v158
	v_rsq_f32_e32 v105, v239
	s_nop 0
	v_mul_f32_e32 v104, 0xbfb8aa3b, v105
	v_pk_mul_f32 v[92:93], v[92:93], v[104:105] op_sel_hi:[1,0]
	v_pk_mul_f32 v[90:91], v[90:91], v[104:105] op_sel_hi:[1,0]
	v_pk_mul_f32 v[84:85], v[84:85], v[104:105] op_sel_hi:[1,0]
	v_pk_mul_f32 v[82:83], v[82:83], v[104:105] op_sel_hi:[1,0]
	v_exp_f32_e32 v90, v90
	v_exp_f32_e32 v91, v91
	v_exp_f32_e32 v92, v92
	v_exp_f32_e32 v93, v93
	v_exp_f32_e32 v82, v82
	v_exp_f32_e32 v83, v83
	v_exp_f32_e32 v84, v84
	v_exp_f32_e32 v85, v85
	v_pk_fma_f32 v[90:91], v[90:91], v[238:239], v[238:239] op_sel:[0,1,1] op_sel_hi:[1,1,1]
	v_pk_fma_f32 v[92:93], v[92:93], v[238:239], v[238:239] op_sel:[0,1,1] op_sel_hi:[1,1,1]
	v_pk_fma_f32 v[250:251], v[82:83], v[238:239], v[238:239] op_sel:[0,1,1] op_sel_hi:[1,1,1]
	v_pk_fma_f32 v[254:255], v[84:85], v[238:239], v[238:239] op_sel:[0,1,1] op_sel_hi:[1,1,1]
	v_rcp_f32_e32 v82, v90
	v_rcp_f32_e32 v83, v91
	v_rcp_f32_e32 v84, v92
	v_rcp_f32_e32 v85, v93
	v_rcp_f32_e32 v90, v250
	v_rcp_f32_e32 v91, v251
	v_rcp_f32_e32 v92, v254
	v_rcp_f32_e32 v93, v255
	v_pk_mul_f32 v[84:85], v[96:97], v[84:85]
	v_pk_mul_f32 v[82:83], v[94:95], v[82:83]
	v_pk_mul_f32 v[88:89], v[88:89], v[92:93]
	v_pk_mul_f32 v[86:87], v[86:87], v[90:91]
	s_mov_b32 s98, 0x2c000
	v_lshl_add_u64 v[100:101], v[240:241], 0, s[98:99]
	v_cvt_pk_bf16_f32 v82, v82, v83
	v_cvt_pk_bf16_f32 v83, v84, v85
	v_cvt_pk_bf16_f32 v84, v86, v87
	v_cvt_pk_bf16_f32 v85, v88, v89
	global_store_dwordx4 v[100:101], v[82:85], off
	s_nop 0
	s_nop 0
	s_mov_b32 s98, 0x42000
	v_lshl_add_u64 v[82:83], v[240:241], 0, s[98:99]
	v_fmamk_f32 v239, v234, 0x3a800000, v158
	v_rsq_f32_e32 v89, v239
	s_nop 0
	v_mul_f32_e32 v88, 0xbfb8aa3b, v89
	v_pk_mul_f32 v[76:77], v[76:77], v[88:89] op_sel_hi:[1,0]
	v_pk_mul_f32 v[74:75], v[74:75], v[88:89] op_sel_hi:[1,0]
	v_pk_mul_f32 v[68:69], v[68:69], v[88:89] op_sel_hi:[1,0]
	v_pk_mul_f32 v[66:67], v[66:67], v[88:89] op_sel_hi:[1,0]
	v_exp_f32_e32 v74, v74
	v_exp_f32_e32 v75, v75
	v_exp_f32_e32 v76, v76
	v_exp_f32_e32 v77, v77
	v_exp_f32_e32 v66, v66
	v_exp_f32_e32 v67, v67
	v_exp_f32_e32 v68, v68
	v_exp_f32_e32 v69, v69
	v_pk_fma_f32 v[74:75], v[74:75], v[238:239], v[238:239] op_sel:[0,1,1] op_sel_hi:[1,1,1]
	v_pk_fma_f32 v[76:77], v[76:77], v[238:239], v[238:239] op_sel:[0,1,1] op_sel_hi:[1,1,1]
	v_pk_fma_f32 v[250:251], v[66:67], v[238:239], v[238:239] op_sel:[0,1,1] op_sel_hi:[1,1,1]
	v_pk_fma_f32 v[254:255], v[68:69], v[238:239], v[238:239] op_sel:[0,1,1] op_sel_hi:[1,1,1]
	v_rcp_f32_e32 v66, v74
	v_rcp_f32_e32 v67, v75
	v_rcp_f32_e32 v68, v76
	v_rcp_f32_e32 v69, v77
	v_rcp_f32_e32 v74, v250
	v_rcp_f32_e32 v75, v251
	v_rcp_f32_e32 v76, v254
	v_rcp_f32_e32 v77, v255
	v_pk_mul_f32 v[68:69], v[80:81], v[68:69]
	v_pk_mul_f32 v[66:67], v[78:79], v[66:67]
	v_pk_mul_f32 v[72:73], v[72:73], v[76:77]
	v_pk_mul_f32 v[70:71], v[70:71], v[74:75]
	v_cvt_pk_bf16_f32 v66, v66, v67
	v_cvt_pk_bf16_f32 v67, v68, v69
	v_cvt_pk_bf16_f32 v68, v70, v71
	v_cvt_pk_bf16_f32 v69, v72, v73
	global_store_dwordx4 v[82:83], v[66:69], off
	v_fmamk_f32 v239, v235, 0x3a800000, v158
	v_rsq_f32_e32 v73, v239
	s_nop 0
	v_mul_f32_e32 v72, 0xbfb8aa3b, v73
	v_pk_mul_f32 v[60:61], v[60:61], v[72:73] op_sel_hi:[1,0]
	v_pk_mul_f32 v[58:59], v[58:59], v[72:73] op_sel_hi:[1,0]
	v_pk_mul_f32 v[52:53], v[52:53], v[72:73] op_sel_hi:[1,0]
	v_pk_mul_f32 v[50:51], v[50:51], v[72:73] op_sel_hi:[1,0]
	v_exp_f32_e32 v58, v58
	v_exp_f32_e32 v59, v59
	v_exp_f32_e32 v60, v60
	v_exp_f32_e32 v61, v61
	v_exp_f32_e32 v50, v50
	v_exp_f32_e32 v51, v51
	v_exp_f32_e32 v52, v52
	v_exp_f32_e32 v53, v53
	v_pk_fma_f32 v[58:59], v[58:59], v[238:239], v[238:239] op_sel:[0,1,1] op_sel_hi:[1,1,1]
	v_pk_fma_f32 v[60:61], v[60:61], v[238:239], v[238:239] op_sel:[0,1,1] op_sel_hi:[1,1,1]
	v_pk_fma_f32 v[250:251], v[50:51], v[238:239], v[238:239] op_sel:[0,1,1] op_sel_hi:[1,1,1]
	v_pk_fma_f32 v[254:255], v[52:53], v[238:239], v[238:239] op_sel:[0,1,1] op_sel_hi:[1,1,1]
	v_rcp_f32_e32 v50, v58
	v_rcp_f32_e32 v51, v59
	v_rcp_f32_e32 v52, v60
	v_rcp_f32_e32 v53, v61
	v_rcp_f32_e32 v58, v250
	v_rcp_f32_e32 v59, v251
	v_rcp_f32_e32 v60, v254
	v_rcp_f32_e32 v61, v255
	v_pk_mul_f32 v[52:53], v[64:65], v[52:53]
	v_pk_mul_f32 v[50:51], v[62:63], v[50:51]
	v_pk_mul_f32 v[56:57], v[56:57], v[60:61]
	v_pk_mul_f32 v[54:55], v[54:55], v[58:59]
	s_mov_b32 s98, 0xb0000
	v_lshl_add_u64 v[68:69], v[240:241], 0, s[98:99]
	v_cvt_pk_bf16_f32 v50, v50, v51
	v_cvt_pk_bf16_f32 v51, v52, v53
	v_cvt_pk_bf16_f32 v52, v54, v55
	v_cvt_pk_bf16_f32 v53, v56, v57
	global_store_dwordx4 v[68:69], v[50:53], off
	v_fmamk_f32 v239, v236, 0x3a800000, v158
	v_rsq_f32_e32 v57, v239
	s_nop 0
	v_mul_f32_e32 v56, 0xbfb8aa3b, v57
	v_pk_mul_f32 v[44:45], v[44:45], v[56:57] op_sel_hi:[1,0]
	v_pk_mul_f32 v[42:43], v[42:43], v[56:57] op_sel_hi:[1,0]
	v_pk_mul_f32 v[36:37], v[36:37], v[56:57] op_sel_hi:[1,0]
	v_pk_mul_f32 v[34:35], v[34:35], v[56:57] op_sel_hi:[1,0]
	v_exp_f32_e32 v42, v42
	v_exp_f32_e32 v43, v43
	v_exp_f32_e32 v44, v44
	v_exp_f32_e32 v45, v45
	v_exp_f32_e32 v34, v34
	v_exp_f32_e32 v35, v35
	v_exp_f32_e32 v36, v36
	v_exp_f32_e32 v37, v37
	v_pk_fma_f32 v[42:43], v[42:43], v[238:239], v[238:239] op_sel:[0,1,1] op_sel_hi:[1,1,1]
	v_pk_fma_f32 v[44:45], v[44:45], v[238:239], v[238:239] op_sel:[0,1,1] op_sel_hi:[1,1,1]
	v_pk_fma_f32 v[250:251], v[34:35], v[238:239], v[238:239] op_sel:[0,1,1] op_sel_hi:[1,1,1]
	v_pk_fma_f32 v[254:255], v[36:37], v[238:239], v[238:239] op_sel:[0,1,1] op_sel_hi:[1,1,1]
	v_rcp_f32_e32 v34, v42
	v_rcp_f32_e32 v35, v43
	v_rcp_f32_e32 v36, v44
	v_rcp_f32_e32 v37, v45
	v_rcp_f32_e32 v42, v250
	v_rcp_f32_e32 v43, v251
	v_rcp_f32_e32 v44, v254
	v_rcp_f32_e32 v45, v255
	v_pk_mul_f32 v[36:37], v[48:49], v[36:37]
	v_pk_mul_f32 v[34:35], v[46:47], v[34:35]
	v_pk_mul_f32 v[40:41], v[40:41], v[44:45]
	v_pk_mul_f32 v[38:39], v[38:39], v[42:43]
	s_mov_b32 s98, 0xc6000
	v_lshl_add_u64 v[52:53], v[240:241], 0, s[98:99]
	v_cvt_pk_bf16_f32 v34, v34, v35
	v_cvt_pk_bf16_f32 v35, v36, v37
	v_cvt_pk_bf16_f32 v36, v38, v39
	v_cvt_pk_bf16_f32 v37, v40, v41
	global_store_dwordx4 v[52:53], v[34:37], off
	v_fmamk_f32 v239, v237, 0x3a800000, v158
	v_rsq_f32_e32 v41, v239
	s_nop 0
	v_mul_f32_e32 v40, 0xbfb8aa3b, v41
	v_pk_mul_f32 v[28:29], v[28:29], v[40:41] op_sel_hi:[1,0]
	v_pk_mul_f32 v[26:27], v[26:27], v[40:41] op_sel_hi:[1,0]
	v_pk_mul_f32 v[20:21], v[20:21], v[40:41] op_sel_hi:[1,0]
	v_pk_mul_f32 v[18:19], v[18:19], v[40:41] op_sel_hi:[1,0]
	v_exp_f32_e32 v26, v26
	v_exp_f32_e32 v27, v27
	v_exp_f32_e32 v28, v28
	v_exp_f32_e32 v29, v29
	v_exp_f32_e32 v18, v18
	v_exp_f32_e32 v19, v19
	v_exp_f32_e32 v20, v20
	v_exp_f32_e32 v21, v21
	v_pk_fma_f32 v[26:27], v[26:27], v[238:239], v[238:239] op_sel:[0,1,1] op_sel_hi:[1,1,1]
	v_pk_fma_f32 v[28:29], v[28:29], v[238:239], v[238:239] op_sel:[0,1,1] op_sel_hi:[1,1,1]
	v_pk_fma_f32 v[250:251], v[18:19], v[238:239], v[238:239] op_sel:[0,1,1] op_sel_hi:[1,1,1]
	v_pk_fma_f32 v[254:255], v[20:21], v[238:239], v[238:239] op_sel:[0,1,1] op_sel_hi:[1,1,1]
	v_rcp_f32_e32 v18, v26
	v_rcp_f32_e32 v19, v27
	v_rcp_f32_e32 v20, v28
	v_rcp_f32_e32 v21, v29
	v_rcp_f32_e32 v26, v250
	v_rcp_f32_e32 v27, v251
	v_rcp_f32_e32 v28, v254
	v_rcp_f32_e32 v29, v255
	v_pk_mul_f32 v[20:21], v[32:33], v[20:21]
	v_pk_mul_f32 v[18:19], v[30:31], v[18:19]
	v_pk_mul_f32 v[24:25], v[24:25], v[28:29]
	v_pk_mul_f32 v[22:23], v[22:23], v[26:27]
	s_mov_b32 s98, 0xdc000
	v_lshl_add_u64 v[36:37], v[240:241], 0, s[98:99]
	v_cvt_pk_bf16_f32 v18, v18, v19
	v_cvt_pk_bf16_f32 v19, v20, v21
	v_cvt_pk_bf16_f32 v20, v22, v23
	v_cvt_pk_bf16_f32 v21, v24, v25
	global_store_dwordx4 v[36:37], v[18:21], off
	s_nop 0
	s_nop 0
	v_fmamk_f32 v239, v238, 0x3a800000, v158
	v_rsq_f32_e32 v21, v239
	s_nop 0
	v_mul_f32_e32 v20, 0xbfb8aa3b, v21
	v_pk_mul_f32 v[12:13], v[12:13], v[20:21] op_sel_hi:[1,0]
	v_pk_mul_f32 v[10:11], v[10:11], v[20:21] op_sel_hi:[1,0]
	v_pk_mul_f32 v[8:9], v[8:9], v[20:21] op_sel_hi:[1,0]
	v_pk_mul_f32 v[6:7], v[6:7], v[20:21] op_sel_hi:[1,0]
	v_exp_f32_e32 v10, v10
	v_exp_f32_e32 v11, v11
	v_exp_f32_e32 v12, v12
	v_exp_f32_e32 v13, v13
	v_exp_f32_e32 v6, v6
	v_exp_f32_e32 v7, v7
	v_exp_f32_e32 v8, v8
	v_exp_f32_e32 v9, v9
	v_pk_fma_f32 v[10:11], v[10:11], v[238:239], v[238:239] op_sel:[0,1,1] op_sel_hi:[1,1,1]
	v_pk_fma_f32 v[12:13], v[12:13], v[238:239], v[238:239] op_sel:[0,1,1] op_sel_hi:[1,1,1]
	v_pk_fma_f32 v[250:251], v[6:7], v[238:239], v[238:239] op_sel:[0,1,1] op_sel_hi:[1,1,1]
	v_pk_fma_f32 v[254:255], v[8:9], v[238:239], v[238:239] op_sel:[0,1,1] op_sel_hi:[1,1,1]
	v_rcp_f32_e32 v6, v10
	v_rcp_f32_e32 v7, v11
	v_rcp_f32_e32 v8, v12
	v_rcp_f32_e32 v9, v13
	v_rcp_f32_e32 v10, v250
	v_rcp_f32_e32 v11, v251
	v_rcp_f32_e32 v12, v254
	v_rcp_f32_e32 v13, v255
	v_pk_mul_f32 v[8:9], v[16:17], v[8:9]
	v_pk_mul_f32 v[6:7], v[14:15], v[6:7]
	v_pk_mul_f32 v[12:13], v[4:5], v[12:13]
	v_pk_mul_f32 v[4:5], v[2:3], v[10:11]
	s_mov_b32 s98, 0xf2000
	v_lshl_add_u64 v[18:19], v[240:241], 0, s[98:99]
	v_cvt_pk_bf16_f32 v2, v6, v7
	v_cvt_pk_bf16_f32 v3, v8, v9
	v_cvt_pk_bf16_f32 v4, v4, v5
	v_cvt_pk_bf16_f32 v5, v12, v13
	s_mov_b64 s[4:5], -1
	global_store_dwordx4 v[18:19], v[2:5], off
	s_cbranch_vccnz .LBB0_148
	s_andn2_b64 vcc, exec, s[10:11]
	s_cbranch_vccnz .LBB0_147
	s_barrier
	s_branch .LBB0_147

.LBB0_843:
	ds_read_b128 v[160:163], v155
	ds_read_b128 v[164:167], v155 offset:1024
	ds_read_b128 v[168:171], v155 offset:2048
	ds_read_b128 v[172:175], v155 offset:3072
	ds_read_b128 v[176:179], v156
	ds_read_b128 v[180:183], v156 offset:1024
	ds_read_b128 v[184:187], v156 offset:2048
	ds_read_b128 v[188:191], v156 offset:3072
	ds_read_b128 v[192:195], v157
	ds_read_b128 v[196:199], v157 offset:1024
	ds_read_b128 v[200:203], v157 offset:2048
	ds_read_b128 v[204:207], v157 offset:3072
	ds_read_b128 v[208:211], v157 offset:4096
	ds_read_b128 v[212:215], v157 offset:5120
	ds_read_b128 v[216:219], v157 offset:6144
	ds_read_b128 v[220:223], v157 offset:7168
	s_andn2_b64 vcc, exec, s[4:5]
	s_waitcnt vmcnt(0)
	v_fmamk_f32 v239, v149, 0x3a800000, v158
	v_rsq_f32_e32 v149, v239
	s_nop 0
	v_mul_f32_e32 v252, 0xbfb8aa3b, v149
	v_pk_mul_f32 v[120:121], v[120:121], v[252:253] op_sel_hi:[1,0]
	v_pk_mul_f32 v[118:119], v[118:119], v[252:253] op_sel_hi:[1,0]
	v_pk_mul_f32 v[116:117], v[116:117], v[252:253] op_sel_hi:[1,0]
	v_pk_mul_f32 v[114:115], v[114:115], v[252:253] op_sel_hi:[1,0]
	v_exp_f32_e32 v118, v118
	v_exp_f32_e32 v119, v119
	v_exp_f32_e32 v120, v120
	v_exp_f32_e32 v121, v121
	v_exp_f32_e32 v114, v114
	v_exp_f32_e32 v115, v115
	v_exp_f32_e32 v116, v116
	v_exp_f32_e32 v117, v117
	v_pk_fma_f32 v[118:119], v[118:119], v[238:239], v[238:239] op_sel:[0,1,1] op_sel_hi:[1,1,1]
	v_pk_fma_f32 v[120:121], v[120:121], v[238:239], v[238:239] op_sel:[0,1,1] op_sel_hi:[1,1,1]
	v_pk_fma_f32 v[250:251], v[114:115], v[238:239], v[238:239] op_sel:[0,1,1] op_sel_hi:[1,1,1]
	v_pk_fma_f32 v[254:255], v[116:117], v[238:239], v[238:239] op_sel:[0,1,1] op_sel_hi:[1,1,1]
	v_rcp_f32_e32 v114, v118
	v_rcp_f32_e32 v115, v119
	v_rcp_f32_e32 v116, v120
	v_rcp_f32_e32 v117, v121
	v_rcp_f32_e32 v118, v250
	v_rcp_f32_e32 v119, v251
	v_rcp_f32_e32 v120, v254
	v_rcp_f32_e32 v121, v255
	v_pk_mul_f32 v[116:117], v[128:129], v[116:117]
	v_pk_mul_f32 v[114:115], v[126:127], v[114:115]
	v_pk_mul_f32 v[120:121], v[124:125], v[120:121]
	v_pk_mul_f32 v[118:119], v[244:245], v[118:119]
	v_cvt_pk_bf16_f32 v114, v114, v115
	v_cvt_pk_bf16_f32 v115, v116, v117
	v_cvt_pk_bf16_f32 v116, v118, v119
	v_cvt_pk_bf16_f32 v117, v120, v121
	global_store_dwordx4 v[248:249], v[114:117], off
	v_fmamk_f32 v239, v232, 0x3a800000, v158
	v_rsq_f32_e32 v121, v239
	s_nop 0
	v_mul_f32_e32 v120, 0xbfb8aa3b, v121
	v_pk_mul_f32 v[108:109], v[108:109], v[120:121] op_sel_hi:[1,0]
	v_pk_mul_f32 v[106:107], v[106:107], v[120:121] op_sel_hi:[1,0]
	v_pk_mul_f32 v[100:101], v[100:101], v[120:121] op_sel_hi:[1,0]
	v_pk_mul_f32 v[98:99], v[98:99], v[120:121] op_sel_hi:[1,0]
	v_exp_f32_e32 v106, v106
	v_exp_f32_e32 v107, v107
	v_exp_f32_e32 v108, v108
	v_exp_f32_e32 v109, v109
	v_exp_f32_e32 v98, v98
	v_exp_f32_e32 v99, v99
	v_exp_f32_e32 v100, v100
	v_exp_f32_e32 v101, v101
	v_pk_fma_f32 v[106:107], v[106:107], v[238:239], v[238:239] op_sel:[0,1,1] op_sel_hi:[1,1,1]
	v_pk_fma_f32 v[108:109], v[108:109], v[238:239], v[238:239] op_sel:[0,1,1] op_sel_hi:[1,1,1]
	v_pk_fma_f32 v[250:251], v[98:99], v[238:239], v[238:239] op_sel:[0,1,1] op_sel_hi:[1,1,1]
	v_pk_fma_f32 v[254:255], v[100:101], v[238:239], v[238:239] op_sel:[0,1,1] op_sel_hi:[1,1,1]
	v_rcp_f32_e32 v98, v106
	v_rcp_f32_e32 v99, v107
	v_rcp_f32_e32 v100, v108
	v_rcp_f32_e32 v101, v109
	v_rcp_f32_e32 v106, v250
	v_rcp_f32_e32 v107, v251
	v_rcp_f32_e32 v108, v254
	v_rcp_f32_e32 v109, v255
	v_pk_mul_f32 v[100:101], v[112:113], v[100:101]
	v_pk_mul_f32 v[98:99], v[110:111], v[98:99]
	v_pk_mul_f32 v[104:105], v[104:105], v[108:109]
	v_pk_mul_f32 v[102:103], v[102:103], v[106:107]
	s_mov_b32 s98, 0x16000
	v_lshl_add_u64 v[116:117], v[240:241], 0, s[98:99]
	v_cvt_pk_bf16_f32 v98, v98, v99
	v_cvt_pk_bf16_f32 v99, v100, v101
	v_cvt_pk_bf16_f32 v100, v102, v103
	v_cvt_pk_bf16_f32 v101, v104, v105
	global_store_dwordx4 v[116:117], v[98:101], off
	v_fmamk_f32 v239, v233, 0x3a800000, v158
	v_rsq_f32_e32 v105, v239
	s_nop 0
	v_mul_f32_e32 v104, 0xbfb8aa3b, v105
	v_pk_mul_f32 v[92:93], v[92:93], v[104:105] op_sel_hi:[1,0]
	v_pk_mul_f32 v[90:91], v[90:91], v[104:105] op_sel_hi:[1,0]
	v_pk_mul_f32 v[84:85], v[84:85], v[104:105] op_sel_hi:[1,0]
	v_pk_mul_f32 v[82:83], v[82:83], v[104:105] op_sel_hi:[1,0]
	v_exp_f32_e32 v90, v90
	v_exp_f32_e32 v91, v91
	v_exp_f32_e32 v92, v92
	v_exp_f32_e32 v93, v93
	v_exp_f32_e32 v82, v82
	v_exp_f32_e32 v83, v83
	v_exp_f32_e32 v84, v84
	v_exp_f32_e32 v85, v85
	v_pk_fma_f32 v[90:91], v[90:91], v[238:239], v[238:239] op_sel:[0,1,1] op_sel_hi:[1,1,1]
	v_pk_fma_f32 v[92:93], v[92:93], v[238:239], v[238:239] op_sel:[0,1,1] op_sel_hi:[1,1,1]
	v_pk_fma_f32 v[250:251], v[82:83], v[238:239], v[238:239] op_sel:[0,1,1] op_sel_hi:[1,1,1]
	v_pk_fma_f32 v[254:255], v[84:85], v[238:239], v[238:239] op_sel:[0,1,1] op_sel_hi:[1,1,1]
	v_rcp_f32_e32 v82, v90
	v_rcp_f32_e32 v83, v91
	v_rcp_f32_e32 v84, v92
	v_rcp_f32_e32 v85, v93
	v_rcp_f32_e32 v90, v250
	v_rcp_f32_e32 v91, v251
	v_rcp_f32_e32 v92, v254
	v_rcp_f32_e32 v93, v255
	v_pk_mul_f32 v[84:85], v[96:97], v[84:85]
	v_pk_mul_f32 v[82:83], v[94:95], v[82:83]
	v_pk_mul_f32 v[88:89], v[88:89], v[92:93]
	v_pk_mul_f32 v[86:87], v[86:87], v[90:91]
	s_mov_b32 s98, 0x2c000
	v_lshl_add_u64 v[100:101], v[240:241], 0, s[98:99]
	v_cvt_pk_bf16_f32 v82, v82, v83
	v_cvt_pk_bf16_f32 v83, v84, v85
	v_cvt_pk_bf16_f32 v84, v86, v87
	v_cvt_pk_bf16_f32 v85, v88, v89
	global_store_dwordx4 v[100:101], v[82:85], off
	s_nop 0
	s_nop 0
	s_mov_b32 s98, 0x42000
	v_lshl_add_u64 v[82:83], v[240:241], 0, s[98:99]
	v_fmamk_f32 v239, v234, 0x3a800000, v158
	v_rsq_f32_e32 v89, v239
	s_nop 0
	v_mul_f32_e32 v88, 0xbfb8aa3b, v89
	v_pk_mul_f32 v[76:77], v[76:77], v[88:89] op_sel_hi:[1,0]
	v_pk_mul_f32 v[74:75], v[74:75], v[88:89] op_sel_hi:[1,0]
	v_pk_mul_f32 v[68:69], v[68:69], v[88:89] op_sel_hi:[1,0]
	v_pk_mul_f32 v[66:67], v[66:67], v[88:89] op_sel_hi:[1,0]
	v_exp_f32_e32 v74, v74
	v_exp_f32_e32 v75, v75
	v_exp_f32_e32 v76, v76
	v_exp_f32_e32 v77, v77
	v_exp_f32_e32 v66, v66
	v_exp_f32_e32 v67, v67
	v_exp_f32_e32 v68, v68
	v_exp_f32_e32 v69, v69
	v_pk_fma_f32 v[74:75], v[74:75], v[238:239], v[238:239] op_sel:[0,1,1] op_sel_hi:[1,1,1]
	v_pk_fma_f32 v[76:77], v[76:77], v[238:239], v[238:239] op_sel:[0,1,1] op_sel_hi:[1,1,1]
	v_pk_fma_f32 v[250:251], v[66:67], v[238:239], v[238:239] op_sel:[0,1,1] op_sel_hi:[1,1,1]
	v_pk_fma_f32 v[254:255], v[68:69], v[238:239], v[238:239] op_sel:[0,1,1] op_sel_hi:[1,1,1]
	v_rcp_f32_e32 v66, v74
	v_rcp_f32_e32 v67, v75
	v_rcp_f32_e32 v68, v76
	v_rcp_f32_e32 v69, v77
	v_rcp_f32_e32 v74, v250
	v_rcp_f32_e32 v75, v251
	v_rcp_f32_e32 v76, v254
	v_rcp_f32_e32 v77, v255
	v_pk_mul_f32 v[68:69], v[80:81], v[68:69]
	v_pk_mul_f32 v[66:67], v[78:79], v[66:67]
	v_pk_mul_f32 v[72:73], v[72:73], v[76:77]
	v_pk_mul_f32 v[70:71], v[70:71], v[74:75]
	v_cvt_pk_bf16_f32 v66, v66, v67
	v_cvt_pk_bf16_f32 v67, v68, v69
	v_cvt_pk_bf16_f32 v68, v70, v71
	v_cvt_pk_bf16_f32 v69, v72, v73
	global_store_dwordx4 v[82:83], v[66:69], off
	v_fmamk_f32 v239, v235, 0x3a800000, v158
	v_rsq_f32_e32 v73, v239
	s_nop 0
	v_mul_f32_e32 v72, 0xbfb8aa3b, v73
	v_pk_mul_f32 v[60:61], v[60:61], v[72:73] op_sel_hi:[1,0]
	v_pk_mul_f32 v[58:59], v[58:59], v[72:73] op_sel_hi:[1,0]
	v_pk_mul_f32 v[52:53], v[52:53], v[72:73] op_sel_hi:[1,0]
	v_pk_mul_f32 v[50:51], v[50:51], v[72:73] op_sel_hi:[1,0]
	v_exp_f32_e32 v58, v58
	v_exp_f32_e32 v59, v59
	v_exp_f32_e32 v60, v60
	v_exp_f32_e32 v61, v61
	v_exp_f32_e32 v50, v50
	v_exp_f32_e32 v51, v51
	v_exp_f32_e32 v52, v52
	v_exp_f32_e32 v53, v53
	v_pk_fma_f32 v[58:59], v[58:59], v[238:239], v[238:239] op_sel:[0,1,1] op_sel_hi:[1,1,1]
	v_pk_fma_f32 v[60:61], v[60:61], v[238:239], v[238:239] op_sel:[0,1,1] op_sel_hi:[1,1,1]
	v_pk_fma_f32 v[250:251], v[50:51], v[238:239], v[238:239] op_sel:[0,1,1] op_sel_hi:[1,1,1]
	v_pk_fma_f32 v[254:255], v[52:53], v[238:239], v[238:239] op_sel:[0,1,1] op_sel_hi:[1,1,1]
	v_rcp_f32_e32 v50, v58
	v_rcp_f32_e32 v51, v59
	v_rcp_f32_e32 v52, v60
	v_rcp_f32_e32 v53, v61
	v_rcp_f32_e32 v58, v250
	v_rcp_f32_e32 v59, v251
	v_rcp_f32_e32 v60, v254
	v_rcp_f32_e32 v61, v255
	v_pk_mul_f32 v[52:53], v[64:65], v[52:53]
	v_pk_mul_f32 v[50:51], v[62:63], v[50:51]
	v_pk_mul_f32 v[56:57], v[56:57], v[60:61]
	v_pk_mul_f32 v[54:55], v[54:55], v[58:59]
	s_mov_b32 s98, 0xb0000
	v_lshl_add_u64 v[68:69], v[240:241], 0, s[98:99]
	v_cvt_pk_bf16_f32 v50, v50, v51
	v_cvt_pk_bf16_f32 v51, v52, v53
	v_cvt_pk_bf16_f32 v52, v54, v55
	v_cvt_pk_bf16_f32 v53, v56, v57
	global_store_dwordx4 v[68:69], v[50:53], off
	v_fmamk_f32 v239, v236, 0x3a800000, v158
	v_rsq_f32_e32 v57, v239
	s_nop 0
	v_mul_f32_e32 v56, 0xbfb8aa3b, v57
	v_pk_mul_f32 v[44:45], v[44:45], v[56:57] op_sel_hi:[1,0]
	v_pk_mul_f32 v[42:43], v[42:43], v[56:57] op_sel_hi:[1,0]
	v_pk_mul_f32 v[36:37], v[36:37], v[56:57] op_sel_hi:[1,0]
	v_pk_mul_f32 v[34:35], v[34:35], v[56:57] op_sel_hi:[1,0]
	v_exp_f32_e32 v42, v42
	v_exp_f32_e32 v43, v43
	v_exp_f32_e32 v44, v44
	v_exp_f32_e32 v45, v45
	v_exp_f32_e32 v34, v34
	v_exp_f32_e32 v35, v35
	v_exp_f32_e32 v36, v36
	v_exp_f32_e32 v37, v37
	v_pk_fma_f32 v[42:43], v[42:43], v[238:239], v[238:239] op_sel:[0,1,1] op_sel_hi:[1,1,1]
	v_pk_fma_f32 v[44:45], v[44:45], v[238:239], v[238:239] op_sel:[0,1,1] op_sel_hi:[1,1,1]
	v_pk_fma_f32 v[250:251], v[34:35], v[238:239], v[238:239] op_sel:[0,1,1] op_sel_hi:[1,1,1]
	v_pk_fma_f32 v[254:255], v[36:37], v[238:239], v[238:239] op_sel:[0,1,1] op_sel_hi:[1,1,1]
	v_rcp_f32_e32 v34, v42
	v_rcp_f32_e32 v35, v43
	v_rcp_f32_e32 v36, v44
	v_rcp_f32_e32 v37, v45
	v_rcp_f32_e32 v42, v250
	v_rcp_f32_e32 v43, v251
	v_rcp_f32_e32 v44, v254
	v_rcp_f32_e32 v45, v255
	v_pk_mul_f32 v[36:37], v[48:49], v[36:37]
	v_pk_mul_f32 v[34:35], v[46:47], v[34:35]
	v_pk_mul_f32 v[40:41], v[40:41], v[44:45]
	v_pk_mul_f32 v[38:39], v[38:39], v[42:43]
	s_mov_b32 s98, 0xc6000
	v_lshl_add_u64 v[52:53], v[240:241], 0, s[98:99]
	v_cvt_pk_bf16_f32 v34, v34, v35
	v_cvt_pk_bf16_f32 v35, v36, v37
	v_cvt_pk_bf16_f32 v36, v38, v39
	v_cvt_pk_bf16_f32 v37, v40, v41
	global_store_dwordx4 v[52:53], v[34:37], off
	v_fmamk_f32 v239, v237, 0x3a800000, v158
	v_rsq_f32_e32 v41, v239
	s_nop 0
	v_mul_f32_e32 v40, 0xbfb8aa3b, v41
	v_pk_mul_f32 v[28:29], v[28:29], v[40:41] op_sel_hi:[1,0]
	v_pk_mul_f32 v[26:27], v[26:27], v[40:41] op_sel_hi:[1,0]
	v_pk_mul_f32 v[20:21], v[20:21], v[40:41] op_sel_hi:[1,0]
	v_pk_mul_f32 v[18:19], v[18:19], v[40:41] op_sel_hi:[1,0]
	v_exp_f32_e32 v26, v26
	v_exp_f32_e32 v27, v27
	v_exp_f32_e32 v28, v28
	v_exp_f32_e32 v29, v29
	v_exp_f32_e32 v18, v18
	v_exp_f32_e32 v19, v19
	v_exp_f32_e32 v20, v20
	v_exp_f32_e32 v21, v21
	v_pk_fma_f32 v[26:27], v[26:27], v[238:239], v[238:239] op_sel:[0,1,1] op_sel_hi:[1,1,1]
	v_pk_fma_f32 v[28:29], v[28:29], v[238:239], v[238:239] op_sel:[0,1,1] op_sel_hi:[1,1,1]
	v_pk_fma_f32 v[250:251], v[18:19], v[238:239], v[238:239] op_sel:[0,1,1] op_sel_hi:[1,1,1]
	v_pk_fma_f32 v[254:255], v[20:21], v[238:239], v[238:239] op_sel:[0,1,1] op_sel_hi:[1,1,1]
	v_rcp_f32_e32 v18, v26
	v_rcp_f32_e32 v19, v27
	v_rcp_f32_e32 v20, v28
	v_rcp_f32_e32 v21, v29
	v_rcp_f32_e32 v26, v250
	v_rcp_f32_e32 v27, v251
	v_rcp_f32_e32 v28, v254
	v_rcp_f32_e32 v29, v255
	v_pk_mul_f32 v[20:21], v[32:33], v[20:21]
	v_pk_mul_f32 v[18:19], v[30:31], v[18:19]
	v_pk_mul_f32 v[24:25], v[24:25], v[28:29]
	v_pk_mul_f32 v[22:23], v[22:23], v[26:27]
	s_mov_b32 s98, 0xdc000
	v_lshl_add_u64 v[36:37], v[240:241], 0, s[98:99]
	v_cvt_pk_bf16_f32 v18, v18, v19
	v_cvt_pk_bf16_f32 v19, v20, v21
	v_cvt_pk_bf16_f32 v20, v22, v23
	v_cvt_pk_bf16_f32 v21, v24, v25
	global_store_dwordx4 v[36:37], v[18:21], off
	s_nop 0
	s_nop 0
	v_fmamk_f32 v239, v238, 0x3a800000, v158
	v_rsq_f32_e32 v21, v239
	s_nop 0
	v_mul_f32_e32 v20, 0xbfb8aa3b, v21
	v_pk_mul_f32 v[12:13], v[12:13], v[20:21] op_sel_hi:[1,0]
	v_pk_mul_f32 v[10:11], v[10:11], v[20:21] op_sel_hi:[1,0]
	v_pk_mul_f32 v[8:9], v[8:9], v[20:21] op_sel_hi:[1,0]
	v_pk_mul_f32 v[6:7], v[6:7], v[20:21] op_sel_hi:[1,0]
	v_exp_f32_e32 v10, v10
	v_exp_f32_e32 v11, v11
	v_exp_f32_e32 v12, v12
	v_exp_f32_e32 v13, v13
	v_exp_f32_e32 v6, v6
	v_exp_f32_e32 v7, v7
	v_exp_f32_e32 v8, v8
	v_exp_f32_e32 v9, v9
	v_pk_fma_f32 v[10:11], v[10:11], v[238:239], v[238:239] op_sel:[0,1,1] op_sel_hi:[1,1,1]
	v_pk_fma_f32 v[12:13], v[12:13], v[238:239], v[238:239] op_sel:[0,1,1] op_sel_hi:[1,1,1]
	v_pk_fma_f32 v[250:251], v[6:7], v[238:239], v[238:239] op_sel:[0,1,1] op_sel_hi:[1,1,1]
	v_pk_fma_f32 v[254:255], v[8:9], v[238:239], v[238:239] op_sel:[0,1,1] op_sel_hi:[1,1,1]
	v_rcp_f32_e32 v6, v10
	v_rcp_f32_e32 v7, v11
	v_rcp_f32_e32 v8, v12
	v_rcp_f32_e32 v9, v13
	v_rcp_f32_e32 v10, v250
	v_rcp_f32_e32 v11, v251
	v_rcp_f32_e32 v12, v254
	v_rcp_f32_e32 v13, v255
	v_pk_mul_f32 v[8:9], v[16:17], v[8:9]
	v_pk_mul_f32 v[6:7], v[14:15], v[6:7]
	v_pk_mul_f32 v[12:13], v[4:5], v[12:13]
	v_pk_mul_f32 v[4:5], v[2:3], v[10:11]
	s_mov_b32 s98, 0xf2000
	v_lshl_add_u64 v[18:19], v[240:241], 0, s[98:99]
	v_cvt_pk_bf16_f32 v2, v6, v7
	v_cvt_pk_bf16_f32 v3, v8, v9
	v_cvt_pk_bf16_f32 v4, v4, v5
	v_cvt_pk_bf16_f32 v5, v12, v13
	s_mov_b64 s[4:5], -1
	global_store_dwordx4 v[18:19], v[2:5], off
	s_cbranch_vccnz .LBB0_836
	s_andn2_b64 vcc, exec, s[8:9]
	s_cbranch_vccnz .LBB0_835
	s_barrier
	s_branch .LBB0_835

.LBB0_1133:
	ds_read_b128 v[160:163], v155
	ds_read_b128 v[164:167], v155 offset:1024
	ds_read_b128 v[168:171], v155 offset:2048
	ds_read_b128 v[172:175], v155 offset:3072
	ds_read_b128 v[176:179], v156
	ds_read_b128 v[180:183], v156 offset:1024
	ds_read_b128 v[184:187], v156 offset:2048
	ds_read_b128 v[188:191], v156 offset:3072
	ds_read_b128 v[192:195], v157
	ds_read_b128 v[196:199], v157 offset:1024
	ds_read_b128 v[200:203], v157 offset:2048
	ds_read_b128 v[204:207], v157 offset:3072
	ds_read_b128 v[208:211], v157 offset:4096
	ds_read_b128 v[212:215], v157 offset:5120
	ds_read_b128 v[216:219], v157 offset:6144
	ds_read_b128 v[220:223], v157 offset:7168
	s_andn2_b64 vcc, exec, s[4:5]
	s_waitcnt vmcnt(0)
	v_fmamk_f32 v239, v149, 0x3a800000, v158
	v_rsq_f32_e32 v149, v239
	s_nop 0
	v_mul_f32_e32 v252, 0xbfb8aa3b, v149
	v_pk_mul_f32 v[120:121], v[120:121], v[252:253] op_sel_hi:[1,0]
	v_pk_mul_f32 v[118:119], v[118:119], v[252:253] op_sel_hi:[1,0]
	v_pk_mul_f32 v[116:117], v[116:117], v[252:253] op_sel_hi:[1,0]
	v_pk_mul_f32 v[114:115], v[114:115], v[252:253] op_sel_hi:[1,0]
	v_exp_f32_e32 v118, v118
	v_exp_f32_e32 v119, v119
	v_exp_f32_e32 v120, v120
	v_exp_f32_e32 v121, v121
	v_exp_f32_e32 v114, v114
	v_exp_f32_e32 v115, v115
	v_exp_f32_e32 v116, v116
	v_exp_f32_e32 v117, v117
	v_pk_fma_f32 v[118:119], v[118:119], v[238:239], v[238:239] op_sel:[0,1,1] op_sel_hi:[1,1,1]
	v_pk_fma_f32 v[120:121], v[120:121], v[238:239], v[238:239] op_sel:[0,1,1] op_sel_hi:[1,1,1]
	v_pk_fma_f32 v[250:251], v[114:115], v[238:239], v[238:239] op_sel:[0,1,1] op_sel_hi:[1,1,1]
	v_pk_fma_f32 v[254:255], v[116:117], v[238:239], v[238:239] op_sel:[0,1,1] op_sel_hi:[1,1,1]
	v_rcp_f32_e32 v114, v118
	v_rcp_f32_e32 v115, v119
	v_rcp_f32_e32 v116, v120
	v_rcp_f32_e32 v117, v121
	v_rcp_f32_e32 v118, v250
	v_rcp_f32_e32 v119, v251
	v_rcp_f32_e32 v120, v254
	v_rcp_f32_e32 v121, v255
	v_pk_mul_f32 v[116:117], v[128:129], v[116:117]
	v_pk_mul_f32 v[114:115], v[126:127], v[114:115]
	v_pk_mul_f32 v[120:121], v[124:125], v[120:121]
	v_pk_mul_f32 v[118:119], v[244:245], v[118:119]
	v_cvt_pk_bf16_f32 v114, v114, v115
	v_cvt_pk_bf16_f32 v115, v116, v117
	v_cvt_pk_bf16_f32 v116, v118, v119
	v_cvt_pk_bf16_f32 v117, v120, v121
	global_store_dwordx4 v[248:249], v[114:117], off
	v_fmamk_f32 v239, v232, 0x3a800000, v158
	v_rsq_f32_e32 v121, v239
	s_nop 0
	v_mul_f32_e32 v120, 0xbfb8aa3b, v121
	v_pk_mul_f32 v[108:109], v[108:109], v[120:121] op_sel_hi:[1,0]
	v_pk_mul_f32 v[106:107], v[106:107], v[120:121] op_sel_hi:[1,0]
	v_pk_mul_f32 v[100:101], v[100:101], v[120:121] op_sel_hi:[1,0]
	v_pk_mul_f32 v[98:99], v[98:99], v[120:121] op_sel_hi:[1,0]
	v_exp_f32_e32 v106, v106
	v_exp_f32_e32 v107, v107
	v_exp_f32_e32 v108, v108
	v_exp_f32_e32 v109, v109
	v_exp_f32_e32 v98, v98
	v_exp_f32_e32 v99, v99
	v_exp_f32_e32 v100, v100
	v_exp_f32_e32 v101, v101
	v_pk_fma_f32 v[106:107], v[106:107], v[238:239], v[238:239] op_sel:[0,1,1] op_sel_hi:[1,1,1]
	v_pk_fma_f32 v[108:109], v[108:109], v[238:239], v[238:239] op_sel:[0,1,1] op_sel_hi:[1,1,1]
	v_pk_fma_f32 v[250:251], v[98:99], v[238:239], v[238:239] op_sel:[0,1,1] op_sel_hi:[1,1,1]
	v_pk_fma_f32 v[254:255], v[100:101], v[238:239], v[238:239] op_sel:[0,1,1] op_sel_hi:[1,1,1]
	v_rcp_f32_e32 v98, v106
	v_rcp_f32_e32 v99, v107
	v_rcp_f32_e32 v100, v108
	v_rcp_f32_e32 v101, v109
	v_rcp_f32_e32 v106, v250
	v_rcp_f32_e32 v107, v251
	v_rcp_f32_e32 v108, v254
	v_rcp_f32_e32 v109, v255
	v_pk_mul_f32 v[100:101], v[112:113], v[100:101]
	v_pk_mul_f32 v[98:99], v[110:111], v[98:99]
	v_pk_mul_f32 v[104:105], v[104:105], v[108:109]
	v_pk_mul_f32 v[102:103], v[102:103], v[106:107]
	s_mov_b32 s98, 0x16000
	v_lshl_add_u64 v[116:117], v[240:241], 0, s[98:99]
	v_cvt_pk_bf16_f32 v98, v98, v99
	v_cvt_pk_bf16_f32 v99, v100, v101
	v_cvt_pk_bf16_f32 v100, v102, v103
	v_cvt_pk_bf16_f32 v101, v104, v105
	global_store_dwordx4 v[116:117], v[98:101], off
	v_fmamk_f32 v239, v233, 0x3a800000, v158
	v_rsq_f32_e32 v105, v239
	s_nop 0
	v_mul_f32_e32 v104, 0xbfb8aa3b, v105
	v_pk_mul_f32 v[92:93], v[92:93], v[104:105] op_sel_hi:[1,0]
	v_pk_mul_f32 v[90:91], v[90:91], v[104:105] op_sel_hi:[1,0]
	v_pk_mul_f32 v[84:85], v[84:85], v[104:105] op_sel_hi:[1,0]
	v_pk_mul_f32 v[82:83], v[82:83], v[104:105] op_sel_hi:[1,0]
	v_exp_f32_e32 v90, v90
	v_exp_f32_e32 v91, v91
	v_exp_f32_e32 v92, v92
	v_exp_f32_e32 v93, v93
	v_exp_f32_e32 v82, v82
	v_exp_f32_e32 v83, v83
	v_exp_f32_e32 v84, v84
	v_exp_f32_e32 v85, v85
	v_pk_fma_f32 v[90:91], v[90:91], v[238:239], v[238:239] op_sel:[0,1,1] op_sel_hi:[1,1,1]
	v_pk_fma_f32 v[92:93], v[92:93], v[238:239], v[238:239] op_sel:[0,1,1] op_sel_hi:[1,1,1]
	v_pk_fma_f32 v[250:251], v[82:83], v[238:239], v[238:239] op_sel:[0,1,1] op_sel_hi:[1,1,1]
	v_pk_fma_f32 v[254:255], v[84:85], v[238:239], v[238:239] op_sel:[0,1,1] op_sel_hi:[1,1,1]
	v_rcp_f32_e32 v82, v90
	v_rcp_f32_e32 v83, v91
	v_rcp_f32_e32 v84, v92
	v_rcp_f32_e32 v85, v93
	v_rcp_f32_e32 v90, v250
	v_rcp_f32_e32 v91, v251
	v_rcp_f32_e32 v92, v254
	v_rcp_f32_e32 v93, v255
	v_pk_mul_f32 v[84:85], v[96:97], v[84:85]
	v_pk_mul_f32 v[82:83], v[94:95], v[82:83]
	v_pk_mul_f32 v[88:89], v[88:89], v[92:93]
	v_pk_mul_f32 v[86:87], v[86:87], v[90:91]
	s_mov_b32 s98, 0x2c000
	v_lshl_add_u64 v[100:101], v[240:241], 0, s[98:99]
	v_cvt_pk_bf16_f32 v82, v82, v83
	v_cvt_pk_bf16_f32 v83, v84, v85
	v_cvt_pk_bf16_f32 v84, v86, v87
	v_cvt_pk_bf16_f32 v85, v88, v89
	global_store_dwordx4 v[100:101], v[82:85], off
	s_nop 0
	s_nop 0
	s_mov_b32 s98, 0x42000
	v_lshl_add_u64 v[82:83], v[240:241], 0, s[98:99]
	v_fmamk_f32 v239, v234, 0x3a800000, v158
	v_rsq_f32_e32 v89, v239
	s_nop 0
	v_mul_f32_e32 v88, 0xbfb8aa3b, v89
	v_pk_mul_f32 v[76:77], v[76:77], v[88:89] op_sel_hi:[1,0]
	v_pk_mul_f32 v[74:75], v[74:75], v[88:89] op_sel_hi:[1,0]
	v_pk_mul_f32 v[68:69], v[68:69], v[88:89] op_sel_hi:[1,0]
	v_pk_mul_f32 v[66:67], v[66:67], v[88:89] op_sel_hi:[1,0]
	v_exp_f32_e32 v74, v74
	v_exp_f32_e32 v75, v75
	v_exp_f32_e32 v76, v76
	v_exp_f32_e32 v77, v77
	v_exp_f32_e32 v66, v66
	v_exp_f32_e32 v67, v67
	v_exp_f32_e32 v68, v68
	v_exp_f32_e32 v69, v69
	v_pk_fma_f32 v[74:75], v[74:75], v[238:239], v[238:239] op_sel:[0,1,1] op_sel_hi:[1,1,1]
	v_pk_fma_f32 v[76:77], v[76:77], v[238:239], v[238:239] op_sel:[0,1,1] op_sel_hi:[1,1,1]
	v_pk_fma_f32 v[250:251], v[66:67], v[238:239], v[238:239] op_sel:[0,1,1] op_sel_hi:[1,1,1]
	v_pk_fma_f32 v[254:255], v[68:69], v[238:239], v[238:239] op_sel:[0,1,1] op_sel_hi:[1,1,1]
	v_rcp_f32_e32 v66, v74
	v_rcp_f32_e32 v67, v75
	v_rcp_f32_e32 v68, v76
	v_rcp_f32_e32 v69, v77
	v_rcp_f32_e32 v74, v250
	v_rcp_f32_e32 v75, v251
	v_rcp_f32_e32 v76, v254
	v_rcp_f32_e32 v77, v255
	v_pk_mul_f32 v[68:69], v[80:81], v[68:69]
	v_pk_mul_f32 v[66:67], v[78:79], v[66:67]
	v_pk_mul_f32 v[72:73], v[72:73], v[76:77]
	v_pk_mul_f32 v[70:71], v[70:71], v[74:75]
	v_cvt_pk_bf16_f32 v66, v66, v67
	v_cvt_pk_bf16_f32 v67, v68, v69
	v_cvt_pk_bf16_f32 v68, v70, v71
	v_cvt_pk_bf16_f32 v69, v72, v73
	global_store_dwordx4 v[82:83], v[66:69], off
	v_fmamk_f32 v239, v235, 0x3a800000, v158
	v_rsq_f32_e32 v73, v239
	s_nop 0
	v_mul_f32_e32 v72, 0xbfb8aa3b, v73
	v_pk_mul_f32 v[60:61], v[60:61], v[72:73] op_sel_hi:[1,0]
	v_pk_mul_f32 v[58:59], v[58:59], v[72:73] op_sel_hi:[1,0]
	v_pk_mul_f32 v[52:53], v[52:53], v[72:73] op_sel_hi:[1,0]
	v_pk_mul_f32 v[50:51], v[50:51], v[72:73] op_sel_hi:[1,0]
	v_exp_f32_e32 v58, v58
	v_exp_f32_e32 v59, v59
	v_exp_f32_e32 v60, v60
	v_exp_f32_e32 v61, v61
	v_exp_f32_e32 v50, v50
	v_exp_f32_e32 v51, v51
	v_exp_f32_e32 v52, v52
	v_exp_f32_e32 v53, v53
	v_pk_fma_f32 v[58:59], v[58:59], v[238:239], v[238:239] op_sel:[0,1,1] op_sel_hi:[1,1,1]
	v_pk_fma_f32 v[60:61], v[60:61], v[238:239], v[238:239] op_sel:[0,1,1] op_sel_hi:[1,1,1]
	v_pk_fma_f32 v[250:251], v[50:51], v[238:239], v[238:239] op_sel:[0,1,1] op_sel_hi:[1,1,1]
	v_pk_fma_f32 v[254:255], v[52:53], v[238:239], v[238:239] op_sel:[0,1,1] op_sel_hi:[1,1,1]
	v_rcp_f32_e32 v50, v58
	v_rcp_f32_e32 v51, v59
	v_rcp_f32_e32 v52, v60
	v_rcp_f32_e32 v53, v61
	v_rcp_f32_e32 v58, v250
	v_rcp_f32_e32 v59, v251
	v_rcp_f32_e32 v60, v254
	v_rcp_f32_e32 v61, v255
	v_pk_mul_f32 v[52:53], v[64:65], v[52:53]
	v_pk_mul_f32 v[50:51], v[62:63], v[50:51]
	v_pk_mul_f32 v[56:57], v[56:57], v[60:61]
	v_pk_mul_f32 v[54:55], v[54:55], v[58:59]
	s_mov_b32 s98, 0xb0000
	v_lshl_add_u64 v[68:69], v[240:241], 0, s[98:99]
	v_cvt_pk_bf16_f32 v50, v50, v51
	v_cvt_pk_bf16_f32 v51, v52, v53
	v_cvt_pk_bf16_f32 v52, v54, v55
	v_cvt_pk_bf16_f32 v53, v56, v57
	global_store_dwordx4 v[68:69], v[50:53], off
	v_fmamk_f32 v239, v236, 0x3a800000, v158
	v_rsq_f32_e32 v57, v239
	s_nop 0
	v_mul_f32_e32 v56, 0xbfb8aa3b, v57
	v_pk_mul_f32 v[44:45], v[44:45], v[56:57] op_sel_hi:[1,0]
	v_pk_mul_f32 v[42:43], v[42:43], v[56:57] op_sel_hi:[1,0]
	v_pk_mul_f32 v[36:37], v[36:37], v[56:57] op_sel_hi:[1,0]
	v_pk_mul_f32 v[34:35], v[34:35], v[56:57] op_sel_hi:[1,0]
	v_exp_f32_e32 v42, v42
	v_exp_f32_e32 v43, v43
	v_exp_f32_e32 v44, v44
	v_exp_f32_e32 v45, v45
	v_exp_f32_e32 v34, v34
	v_exp_f32_e32 v35, v35
	v_exp_f32_e32 v36, v36
	v_exp_f32_e32 v37, v37
	v_pk_fma_f32 v[42:43], v[42:43], v[238:239], v[238:239] op_sel:[0,1,1] op_sel_hi:[1,1,1]
	v_pk_fma_f32 v[44:45], v[44:45], v[238:239], v[238:239] op_sel:[0,1,1] op_sel_hi:[1,1,1]
	v_pk_fma_f32 v[250:251], v[34:35], v[238:239], v[238:239] op_sel:[0,1,1] op_sel_hi:[1,1,1]
	v_pk_fma_f32 v[254:255], v[36:37], v[238:239], v[238:239] op_sel:[0,1,1] op_sel_hi:[1,1,1]
	v_rcp_f32_e32 v34, v42
	v_rcp_f32_e32 v35, v43
	v_rcp_f32_e32 v36, v44
	v_rcp_f32_e32 v37, v45
	v_rcp_f32_e32 v42, v250
	v_rcp_f32_e32 v43, v251
	v_rcp_f32_e32 v44, v254
	v_rcp_f32_e32 v45, v255
	v_pk_mul_f32 v[36:37], v[48:49], v[36:37]
	v_pk_mul_f32 v[34:35], v[46:47], v[34:35]
	v_pk_mul_f32 v[40:41], v[40:41], v[44:45]
	v_pk_mul_f32 v[38:39], v[38:39], v[42:43]
	s_mov_b32 s98, 0xc6000
	v_lshl_add_u64 v[52:53], v[240:241], 0, s[98:99]
	v_cvt_pk_bf16_f32 v34, v34, v35
	v_cvt_pk_bf16_f32 v35, v36, v37
	v_cvt_pk_bf16_f32 v36, v38, v39
	v_cvt_pk_bf16_f32 v37, v40, v41
	global_store_dwordx4 v[52:53], v[34:37], off
	v_fmamk_f32 v239, v237, 0x3a800000, v158
	v_rsq_f32_e32 v41, v239
	s_nop 0
	v_mul_f32_e32 v40, 0xbfb8aa3b, v41
	v_pk_mul_f32 v[28:29], v[28:29], v[40:41] op_sel_hi:[1,0]
	v_pk_mul_f32 v[26:27], v[26:27], v[40:41] op_sel_hi:[1,0]
	v_pk_mul_f32 v[20:21], v[20:21], v[40:41] op_sel_hi:[1,0]
	v_pk_mul_f32 v[18:19], v[18:19], v[40:41] op_sel_hi:[1,0]
	v_exp_f32_e32 v26, v26
	v_exp_f32_e32 v27, v27
	v_exp_f32_e32 v28, v28
	v_exp_f32_e32 v29, v29
	v_exp_f32_e32 v18, v18
	v_exp_f32_e32 v19, v19
	v_exp_f32_e32 v20, v20
	v_exp_f32_e32 v21, v21
	v_pk_fma_f32 v[26:27], v[26:27], v[238:239], v[238:239] op_sel:[0,1,1] op_sel_hi:[1,1,1]
	v_pk_fma_f32 v[28:29], v[28:29], v[238:239], v[238:239] op_sel:[0,1,1] op_sel_hi:[1,1,1]
	v_pk_fma_f32 v[250:251], v[18:19], v[238:239], v[238:239] op_sel:[0,1,1] op_sel_hi:[1,1,1]
	v_pk_fma_f32 v[254:255], v[20:21], v[238:239], v[238:239] op_sel:[0,1,1] op_sel_hi:[1,1,1]
	v_rcp_f32_e32 v18, v26
	v_rcp_f32_e32 v19, v27
	v_rcp_f32_e32 v20, v28
	v_rcp_f32_e32 v21, v29
	v_rcp_f32_e32 v26, v250
	v_rcp_f32_e32 v27, v251
	v_rcp_f32_e32 v28, v254
	v_rcp_f32_e32 v29, v255
	v_pk_mul_f32 v[20:21], v[32:33], v[20:21]
	v_pk_mul_f32 v[18:19], v[30:31], v[18:19]
	v_pk_mul_f32 v[24:25], v[24:25], v[28:29]
	v_pk_mul_f32 v[22:23], v[22:23], v[26:27]
	s_mov_b32 s98, 0xdc000
	v_lshl_add_u64 v[36:37], v[240:241], 0, s[98:99]
	v_cvt_pk_bf16_f32 v18, v18, v19
	v_cvt_pk_bf16_f32 v19, v20, v21
	v_cvt_pk_bf16_f32 v20, v22, v23
	v_cvt_pk_bf16_f32 v21, v24, v25
	global_store_dwordx4 v[36:37], v[18:21], off
	s_nop 0
	s_nop 0
	v_fmamk_f32 v239, v238, 0x3a800000, v158
	v_rsq_f32_e32 v21, v239
	s_nop 0
	v_mul_f32_e32 v20, 0xbfb8aa3b, v21
	v_pk_mul_f32 v[12:13], v[12:13], v[20:21] op_sel_hi:[1,0]
	v_pk_mul_f32 v[10:11], v[10:11], v[20:21] op_sel_hi:[1,0]
	v_pk_mul_f32 v[8:9], v[8:9], v[20:21] op_sel_hi:[1,0]
	v_pk_mul_f32 v[6:7], v[6:7], v[20:21] op_sel_hi:[1,0]
	v_exp_f32_e32 v10, v10
	v_exp_f32_e32 v11, v11
	v_exp_f32_e32 v12, v12
	v_exp_f32_e32 v13, v13
	v_exp_f32_e32 v6, v6
	v_exp_f32_e32 v7, v7
	v_exp_f32_e32 v8, v8
	v_exp_f32_e32 v9, v9
	v_pk_fma_f32 v[10:11], v[10:11], v[238:239], v[238:239] op_sel:[0,1,1] op_sel_hi:[1,1,1]
	v_pk_fma_f32 v[12:13], v[12:13], v[238:239], v[238:239] op_sel:[0,1,1] op_sel_hi:[1,1,1]
	v_pk_fma_f32 v[250:251], v[6:7], v[238:239], v[238:239] op_sel:[0,1,1] op_sel_hi:[1,1,1]
	v_pk_fma_f32 v[254:255], v[8:9], v[238:239], v[238:239] op_sel:[0,1,1] op_sel_hi:[1,1,1]
	v_rcp_f32_e32 v6, v10
	v_rcp_f32_e32 v7, v11
	v_rcp_f32_e32 v8, v12
	v_rcp_f32_e32 v9, v13
	v_rcp_f32_e32 v10, v250
	v_rcp_f32_e32 v11, v251
	v_rcp_f32_e32 v12, v254
	v_rcp_f32_e32 v13, v255
	v_pk_mul_f32 v[8:9], v[16:17], v[8:9]
	v_pk_mul_f32 v[6:7], v[14:15], v[6:7]
	v_pk_mul_f32 v[12:13], v[4:5], v[12:13]
	v_pk_mul_f32 v[4:5], v[2:3], v[10:11]
	s_mov_b32 s98, 0xf2000
	v_lshl_add_u64 v[18:19], v[240:241], 0, s[98:99]
	v_cvt_pk_bf16_f32 v2, v6, v7
	v_cvt_pk_bf16_f32 v3, v8, v9
	v_cvt_pk_bf16_f32 v4, v4, v5
	v_cvt_pk_bf16_f32 v5, v12, v13
	s_mov_b64 s[4:5], -1
	global_store_dwordx4 v[18:19], v[2:5], off
	s_cbranch_vccnz .LBB0_1126
	s_andn2_b64 vcc, exec, s[6:7]
	s_cbranch_vccnz .LBB0_1125
	s_barrier
	s_branch .LBB0_1125
